# stack8: removed compiler's full vmcnt(0) drain at the top of the phase-B GEMM K-loop (other phases run the same template without it)
# speedup vs baseline: 1.0100x; 1.0100x over previous
.LBB0_296:
	s_add_u32 s38, s22, 0xfffc0080
	s_addc_u32 s39, s23, -1
	s_add_i32 s44, 0, 0x10000
	v_add_u32_e32 v140, s44, v240
	s_waitcnt lgkmcnt(0)
	ds_read_b128 v[128:131], v140
	ds_read_b128 v[132:135], v140 offset:1024
	ds_read_b128 v[136:139], v140 offset:2048
	ds_read_b128 v[140:143], v140 offset:3072
	s_cmp_eq_u32 s35, 12
	s_cselect_b32 s43, s37, s39
	s_cselect_b32 s42, s36, s38
	s_cselect_b32 s39, s53, s31
	s_cselect_b32 s38, s52, s3
	v_lshl_add_u64 v[198:199], s[22:23], 0, v[148:149]
	s_add_i32 m0, s59, 0xc000
	ds_read_b128 v[152:155], v241
	ds_read_b128 v[156:159], v241 offset:1024
	ds_read_b128 v[160:163], v241 offset:2048
	ds_read_b128 v[164:167], v241 offset:3072
	ds_read_b128 v[168:171], v241 offset:4096
	ds_read_b128 v[172:175], v241 offset:5120
	ds_read_b128 v[190:193], v241 offset:6144
	ds_read_b128 v[194:197], v241 offset:7168
	global_load_lds_dwordx4 v[198:199], off
	v_lshl_add_u64 v[198:199], s[22:23], 0, v[150:151]
	s_add_i32 m0, s59, 0xe000
	s_nop 0
	global_load_lds_dwordx4 v[198:199], off
	s_waitcnt lgkmcnt(8)
	s_barrier
	s_waitcnt lgkmcnt(0)
	s_setprio 1
	s_waitcnt lgkmcnt(0)
	v_mfma_f32_16x16x32_bf16 v[124:127], v[128:131], v[152:155], v[124:127]
	v_mfma_f32_16x16x32_bf16 v[120:123], v[136:139], v[152:155], v[120:123]
	v_mfma_f32_16x16x32_bf16 v[108:111], v[128:131], v[160:163], v[108:111]
	v_mfma_f32_16x16x32_bf16 v[104:107], v[136:139], v[160:163], v[104:107]
	v_mfma_f32_16x16x32_bf16 v[92:95], v[128:131], v[168:171], v[92:95]
	v_mfma_f32_16x16x32_bf16 v[88:91], v[136:139], v[168:171], v[88:91]
	v_mfma_f32_16x16x32_bf16 v[76:79], v[128:131], v[190:193], v[76:79]
	v_mfma_f32_16x16x32_bf16 v[72:75], v[136:139], v[190:193], v[72:75]
	v_mfma_f32_16x16x32_bf16 v[124:127], v[132:135], v[156:159], v[124:127]
	v_mfma_f32_16x16x32_bf16 v[120:123], v[140:143], v[156:159], v[120:123]
	v_mfma_f32_16x16x32_bf16 v[108:111], v[132:135], v[164:167], v[108:111]
	v_mfma_f32_16x16x32_bf16 v[104:107], v[140:143], v[164:167], v[104:107]
	v_mfma_f32_16x16x32_bf16 v[92:95], v[132:135], v[172:175], v[92:95]
	v_mfma_f32_16x16x32_bf16 v[88:91], v[140:143], v[172:175], v[88:91]
	v_mfma_f32_16x16x32_bf16 v[76:79], v[132:135], v[194:197], v[76:79]
	v_mfma_f32_16x16x32_bf16 v[72:75], v[140:143], v[194:197], v[72:75]
	s_setprio 0
	s_barrier
	s_add_i32 s46, 0, 0x14000
	s_add_i32 s44, s44, s58
	v_add_u32_e32 v176, s46, v240
	v_lshl_add_u64 v[214:215], s[38:39], 0, v[144:145]
	s_mov_b32 m0, s44
	ds_read_b128 v[198:201], v176
	ds_read_b128 v[202:205], v176 offset:1024
	ds_read_b128 v[206:209], v176 offset:2048
	ds_read_b128 v[210:213], v176 offset:3072
	global_load_lds_dwordx4 v[214:215], off
	v_lshl_add_u64 v[216:217], s[38:39], 0, v[146:147]
	s_add_i32 m0, s44, 0x2000
	s_nop 0
	global_load_lds_dwordx4 v[216:217], off
	s_barrier
	s_waitcnt lgkmcnt(0)
	s_setprio 1
	s_waitcnt lgkmcnt(0)
	v_mfma_f32_16x16x32_bf16 v[116:119], v[198:201], v[152:155], v[116:119]
	v_mfma_f32_16x16x32_bf16 v[112:115], v[206:209], v[152:155], v[112:115]
	v_mfma_f32_16x16x32_bf16 v[100:103], v[198:201], v[160:163], v[100:103]
	v_mfma_f32_16x16x32_bf16 v[96:99], v[206:209], v[160:163], v[96:99]
	v_mfma_f32_16x16x32_bf16 v[84:87], v[198:201], v[168:171], v[84:87]
	v_mfma_f32_16x16x32_bf16 v[80:83], v[206:209], v[168:171], v[80:83]
	v_mfma_f32_16x16x32_bf16 v[68:71], v[198:201], v[190:193], v[68:71]
	v_mfma_f32_16x16x32_bf16 v[64:67], v[206:209], v[190:193], v[64:67]
	v_mfma_f32_16x16x32_bf16 v[116:119], v[202:205], v[156:159], v[116:119]
	v_mfma_f32_16x16x32_bf16 v[112:115], v[210:213], v[156:159], v[112:115]
	v_mfma_f32_16x16x32_bf16 v[100:103], v[202:205], v[164:167], v[100:103]
	v_mfma_f32_16x16x32_bf16 v[96:99], v[210:213], v[164:167], v[96:99]
	v_mfma_f32_16x16x32_bf16 v[84:87], v[202:205], v[172:175], v[84:87]
	v_mfma_f32_16x16x32_bf16 v[80:83], v[210:213], v[172:175], v[80:83]
	v_mfma_f32_16x16x32_bf16 v[68:71], v[202:205], v[194:197], v[68:71]
	v_mfma_f32_16x16x32_bf16 v[64:67], v[210:213], v[194:197], v[64:67]
	s_setprio 0
	s_mov_b32 m0, s59
	v_lshl_add_u64 v[218:219], s[42:43], 0, v[144:145]
	s_barrier
	ds_read_b128 v[152:155], v241 offset:16384
	ds_read_b128 v[156:159], v241 offset:17408
	ds_read_b128 v[160:163], v241 offset:18432
	ds_read_b128 v[164:167], v241 offset:19456
	ds_read_b128 v[168:171], v241 offset:20480
	ds_read_b128 v[172:175], v241 offset:21504
	ds_read_b128 v[190:193], v241 offset:22528
	ds_read_b128 v[194:197], v241 offset:23552
	global_load_lds_dwordx4 v[218:219], off
	v_lshl_add_u64 v[220:221], s[42:43], 0, v[146:147]
	s_mov_b32 m0, s60
	s_nop 0
	global_load_lds_dwordx4 v[220:221], off
	s_barrier
	s_waitcnt lgkmcnt(0)
	s_setprio 1
	s_waitcnt lgkmcnt(0)
	v_mfma_f32_16x16x32_bf16 v[60:63], v[128:131], v[152:155], v[60:63]
	v_mfma_f32_16x16x32_bf16 v[56:59], v[136:139], v[152:155], v[56:59]
	v_mfma_f32_16x16x32_bf16 v[44:47], v[128:131], v[160:163], v[44:47]
	v_mfma_f32_16x16x32_bf16 v[40:43], v[136:139], v[160:163], v[40:43]
	v_mfma_f32_16x16x32_bf16 v[28:31], v[128:131], v[168:171], v[28:31]
	v_mfma_f32_16x16x32_bf16 v[24:27], v[136:139], v[168:171], v[24:27]
	v_mfma_f32_16x16x32_bf16 v[12:15], v[128:131], v[190:193], v[12:15]
	v_mfma_f32_16x16x32_bf16 v[8:11], v[136:139], v[190:193], v[8:11]
	v_mfma_f32_16x16x32_bf16 v[60:63], v[132:135], v[156:159], v[60:63]
	v_mfma_f32_16x16x32_bf16 v[56:59], v[140:143], v[156:159], v[56:59]
	v_mfma_f32_16x16x32_bf16 v[44:47], v[132:135], v[164:167], v[44:47]
	v_mfma_f32_16x16x32_bf16 v[40:43], v[140:143], v[164:167], v[40:43]
	v_mfma_f32_16x16x32_bf16 v[28:31], v[132:135], v[172:175], v[28:31]
	v_mfma_f32_16x16x32_bf16 v[24:27], v[140:143], v[172:175], v[24:27]
	v_mfma_f32_16x16x32_bf16 v[12:15], v[132:135], v[194:197], v[12:15]
	v_mfma_f32_16x16x32_bf16 v[8:11], v[140:143], v[194:197], v[8:11]
	s_setprio 0
	s_barrier
	s_add_u32 s44, s38, 0x40000
	s_addc_u32 s45, s39, 0
	s_add_i32 s46, s46, s58
	v_lshl_add_u64 v[128:129], s[44:45], 0, v[144:145]
	s_mov_b32 m0, s46
	s_nop 0
	global_load_lds_dwordx4 v[128:129], off
	v_lshl_add_u64 v[128:129], s[44:45], 0, v[146:147]
	s_add_i32 m0, s46, 0x2000
	s_nop 0
	global_load_lds_dwordx4 v[128:129], off
	s_waitcnt vmcnt(6)
	s_barrier
	s_setprio 1
	v_mfma_f32_16x16x32_bf16 v[52:55], v[198:201], v[152:155], v[52:55]
	v_mfma_f32_16x16x32_bf16 v[48:51], v[206:209], v[152:155], v[48:51]
	v_mfma_f32_16x16x32_bf16 v[36:39], v[198:201], v[160:163], v[36:39]
	v_mfma_f32_16x16x32_bf16 v[32:35], v[206:209], v[160:163], v[32:35]
	v_mfma_f32_16x16x32_bf16 v[20:23], v[198:201], v[168:171], v[20:23]
	v_mfma_f32_16x16x32_bf16 v[16:19], v[206:209], v[168:171], v[16:19]
	v_mfma_f32_16x16x32_bf16 v[4:7], v[198:201], v[190:193], v[4:7]
	v_mfma_f32_16x16x32_bf16 v[0:3], v[206:209], v[190:193], v[0:3]
	v_mfma_f32_16x16x32_bf16 v[52:55], v[202:205], v[156:159], v[52:55]
	v_mfma_f32_16x16x32_bf16 v[48:51], v[210:213], v[156:159], v[48:51]
	v_mfma_f32_16x16x32_bf16 v[36:39], v[202:205], v[164:167], v[36:39]
	v_mfma_f32_16x16x32_bf16 v[32:35], v[210:213], v[164:167], v[32:35]
	v_mfma_f32_16x16x32_bf16 v[20:23], v[202:205], v[172:175], v[20:23]
	v_mfma_f32_16x16x32_bf16 v[16:19], v[210:213], v[172:175], v[16:19]
	v_mfma_f32_16x16x32_bf16 v[4:7], v[202:205], v[194:197], v[4:7]
	v_mfma_f32_16x16x32_bf16 v[0:3], v[210:213], v[194:197], v[0:3]
	s_setprio 0
	s_add_i32 s44, 0, 0x18000
	v_add_u32_e32 v140, s44, v240
	s_barrier
	ds_read_b128 v[128:131], v140
	ds_read_b128 v[132:135], v140 offset:1024
	ds_read_b128 v[136:139], v140 offset:2048
	ds_read_b128 v[140:143], v140 offset:3072
	s_add_u32 s42, s42, 0x40000
	s_addc_u32 s43, s43, 0
	s_mov_b32 m0, s61
	v_lshl_add_u64 v[198:199], s[42:43], 0, v[144:145]
	ds_read_b128 v[152:155], v241 offset:32768
	ds_read_b128 v[156:159], v241 offset:33792
	ds_read_b128 v[160:163], v241 offset:34816
	ds_read_b128 v[164:167], v241 offset:35840
	ds_read_b128 v[168:171], v241 offset:36864
	ds_read_b128 v[172:175], v241 offset:37888
	ds_read_b128 v[190:193], v241 offset:38912
	ds_read_b128 v[194:197], v241 offset:39936
	global_load_lds_dwordx4 v[198:199], off
	v_lshl_add_u64 v[198:199], s[42:43], 0, v[146:147]
	s_mov_b32 m0, s62
	s_nop 0
	global_load_lds_dwordx4 v[198:199], off
	s_waitcnt lgkmcnt(8)
	s_barrier
	s_waitcnt lgkmcnt(0)
	s_setprio 1
	s_waitcnt lgkmcnt(0)
	v_mfma_f32_16x16x32_bf16 v[124:127], v[128:131], v[152:155], v[124:127]
	v_mfma_f32_16x16x32_bf16 v[120:123], v[136:139], v[152:155], v[120:123]
	v_mfma_f32_16x16x32_bf16 v[108:111], v[128:131], v[160:163], v[108:111]
	v_mfma_f32_16x16x32_bf16 v[104:107], v[136:139], v[160:163], v[104:107]
	v_mfma_f32_16x16x32_bf16 v[92:95], v[128:131], v[168:171], v[92:95]
	v_mfma_f32_16x16x32_bf16 v[88:91], v[136:139], v[168:171], v[88:91]
	v_mfma_f32_16x16x32_bf16 v[76:79], v[128:131], v[190:193], v[76:79]
	v_mfma_f32_16x16x32_bf16 v[72:75], v[136:139], v[190:193], v[72:75]
	v_mfma_f32_16x16x32_bf16 v[124:127], v[132:135], v[156:159], v[124:127]
	v_mfma_f32_16x16x32_bf16 v[120:123], v[140:143], v[156:159], v[120:123]
	v_mfma_f32_16x16x32_bf16 v[108:111], v[132:135], v[164:167], v[108:111]
	v_mfma_f32_16x16x32_bf16 v[104:107], v[140:143], v[164:167], v[104:107]
	v_mfma_f32_16x16x32_bf16 v[92:95], v[132:135], v[172:175], v[92:95]
	v_mfma_f32_16x16x32_bf16 v[88:91], v[140:143], v[172:175], v[88:91]
	v_mfma_f32_16x16x32_bf16 v[76:79], v[132:135], v[194:197], v[76:79]
	v_mfma_f32_16x16x32_bf16 v[72:75], v[140:143], v[194:197], v[72:75]
	s_setprio 0
	s_barrier
	s_add_i32 s42, 0, 0x1c000
	s_add_i32 s43, s44, s58
	v_add_u32_e32 v176, s42, v240
	v_lshl_add_u64 v[214:215], v[214:215], 0, s[24:25]
	s_mov_b32 m0, s43
	ds_read_b128 v[198:201], v176
	ds_read_b128 v[202:205], v176 offset:1024
	ds_read_b128 v[206:209], v176 offset:2048
	ds_read_b128 v[210:213], v176 offset:3072
	global_load_lds_dwordx4 v[214:215], off
	v_lshl_add_u64 v[214:215], v[216:217], 0, s[24:25]
	s_add_i32 m0, s43, 0x2000
	s_nop 0
	global_load_lds_dwordx4 v[214:215], off
	s_barrier
	s_waitcnt lgkmcnt(0)
	s_setprio 1
	s_waitcnt lgkmcnt(0)
	v_mfma_f32_16x16x32_bf16 v[116:119], v[198:201], v[152:155], v[116:119]
	v_mfma_f32_16x16x32_bf16 v[112:115], v[206:209], v[152:155], v[112:115]
	v_mfma_f32_16x16x32_bf16 v[100:103], v[198:201], v[160:163], v[100:103]
	v_mfma_f32_16x16x32_bf16 v[96:99], v[206:209], v[160:163], v[96:99]
	v_mfma_f32_16x16x32_bf16 v[84:87], v[198:201], v[168:171], v[84:87]
	v_mfma_f32_16x16x32_bf16 v[80:83], v[206:209], v[168:171], v[80:83]
	v_mfma_f32_16x16x32_bf16 v[68:71], v[198:201], v[190:193], v[68:71]
	v_mfma_f32_16x16x32_bf16 v[64:67], v[206:209], v[190:193], v[64:67]
	v_mfma_f32_16x16x32_bf16 v[116:119], v[202:205], v[156:159], v[116:119]
	v_mfma_f32_16x16x32_bf16 v[112:115], v[210:213], v[156:159], v[112:115]
	v_mfma_f32_16x16x32_bf16 v[100:103], v[202:205], v[164:167], v[100:103]
	v_mfma_f32_16x16x32_bf16 v[96:99], v[210:213], v[164:167], v[96:99]
	v_mfma_f32_16x16x32_bf16 v[84:87], v[202:205], v[172:175], v[84:87]
	v_mfma_f32_16x16x32_bf16 v[80:83], v[210:213], v[172:175], v[80:83]
	v_mfma_f32_16x16x32_bf16 v[68:71], v[202:205], v[194:197], v[68:71]
	v_mfma_f32_16x16x32_bf16 v[64:67], v[210:213], v[194:197], v[64:67]
	s_setprio 0
	s_mov_b32 m0, s64
	v_lshl_add_u64 v[214:215], v[218:219], 0, s[24:25]
	s_barrier
	ds_read_b128 v[152:155], v241 offset:49152
	ds_read_b128 v[156:159], v241 offset:50176
	ds_read_b128 v[160:163], v241 offset:51200
	ds_read_b128 v[164:167], v241 offset:52224
	ds_read_b128 v[168:171], v241 offset:53248
	ds_read_b128 v[172:175], v241 offset:54272
	ds_read_b128 v[190:193], v241 offset:55296
	ds_read_b128 v[194:197], v241 offset:56320
	global_load_lds_dwordx4 v[214:215], off
	v_lshl_add_u64 v[214:215], v[220:221], 0, s[24:25]
	s_mov_b32 m0, s65
	s_nop 0
	global_load_lds_dwordx4 v[214:215], off
	s_barrier
	s_waitcnt lgkmcnt(0)
	s_setprio 1
	s_waitcnt lgkmcnt(0)
	v_mfma_f32_16x16x32_bf16 v[60:63], v[128:131], v[152:155], v[60:63]
	v_mfma_f32_16x16x32_bf16 v[56:59], v[136:139], v[152:155], v[56:59]
	v_mfma_f32_16x16x32_bf16 v[44:47], v[128:131], v[160:163], v[44:47]
	v_mfma_f32_16x16x32_bf16 v[40:43], v[136:139], v[160:163], v[40:43]
	v_mfma_f32_16x16x32_bf16 v[28:31], v[128:131], v[168:171], v[28:31]
	v_mfma_f32_16x16x32_bf16 v[24:27], v[136:139], v[168:171], v[24:27]
	v_mfma_f32_16x16x32_bf16 v[12:15], v[128:131], v[190:193], v[12:15]
	v_mfma_f32_16x16x32_bf16 v[8:11], v[136:139], v[190:193], v[8:11]
	v_mfma_f32_16x16x32_bf16 v[60:63], v[132:135], v[156:159], v[60:63]
	v_mfma_f32_16x16x32_bf16 v[56:59], v[140:143], v[156:159], v[56:59]
	v_mfma_f32_16x16x32_bf16 v[44:47], v[132:135], v[164:167], v[44:47]
	v_mfma_f32_16x16x32_bf16 v[40:43], v[140:143], v[164:167], v[40:43]
	v_mfma_f32_16x16x32_bf16 v[28:31], v[132:135], v[172:175], v[28:31]
	v_mfma_f32_16x16x32_bf16 v[24:27], v[140:143], v[172:175], v[24:27]
	v_mfma_f32_16x16x32_bf16 v[12:15], v[132:135], v[194:197], v[12:15]
	v_mfma_f32_16x16x32_bf16 v[8:11], v[140:143], v[194:197], v[8:11]
	s_setprio 0
	s_barrier
	s_add_u32 s38, s38, 0x40080
	s_addc_u32 s39, s39, 0
	s_add_i32 s42, s42, s58
	v_lshl_add_u64 v[128:129], s[38:39], 0, v[144:145]
	s_mov_b32 m0, s42
	s_nop 0
	global_load_lds_dwordx4 v[128:129], off
	v_lshl_add_u64 v[128:129], s[38:39], 0, v[146:147]
	s_add_i32 m0, s42, 0x2000
	s_nop 0
	global_load_lds_dwordx4 v[128:129], off
	s_waitcnt vmcnt(6)
	s_barrier
	s_setprio 1
	v_mfma_f32_16x16x32_bf16 v[52:55], v[198:201], v[152:155], v[52:55]
	v_mfma_f32_16x16x32_bf16 v[48:51], v[206:209], v[152:155], v[48:51]
	v_mfma_f32_16x16x32_bf16 v[36:39], v[198:201], v[160:163], v[36:39]
	v_mfma_f32_16x16x32_bf16 v[32:35], v[206:209], v[160:163], v[32:35]
	v_mfma_f32_16x16x32_bf16 v[20:23], v[198:201], v[168:171], v[20:23]
	v_mfma_f32_16x16x32_bf16 v[16:19], v[206:209], v[168:171], v[16:19]
	v_mfma_f32_16x16x32_bf16 v[4:7], v[198:201], v[190:193], v[4:7]
	v_mfma_f32_16x16x32_bf16 v[0:3], v[206:209], v[190:193], v[0:3]
	v_mfma_f32_16x16x32_bf16 v[52:55], v[202:205], v[156:159], v[52:55]
	v_mfma_f32_16x16x32_bf16 v[48:51], v[210:213], v[156:159], v[48:51]
	v_mfma_f32_16x16x32_bf16 v[36:39], v[202:205], v[164:167], v[36:39]
	v_mfma_f32_16x16x32_bf16 v[32:35], v[210:213], v[164:167], v[32:35]
	v_mfma_f32_16x16x32_bf16 v[20:23], v[202:205], v[172:175], v[20:23]
	v_mfma_f32_16x16x32_bf16 v[16:19], v[210:213], v[172:175], v[16:19]
	v_mfma_f32_16x16x32_bf16 v[4:7], v[202:205], v[194:197], v[4:7]
	v_mfma_f32_16x16x32_bf16 v[0:3], v[210:213], v[194:197], v[0:3]
	s_setprio 0
	s_add_i32 s35, s35, 2
	s_add_u32 s22, s22, 0x100
	s_addc_u32 s23, s23, 0
	s_add_u32 s3, s3, 0x100
	s_addc_u32 s31, s31, 0
	s_cmp_gt_u32 s35, 13
	s_barrier
	s_cbranch_scc0 .LBB0_296
	v_mov_b32_e32 v153, v238
	s_mov_b32 s3, s57
	v_mov_b32_e32 v157, v239
	s_mov_b32 s31, s63
	s_lshl_b32 s22, s2, 8
	s_lshl_b32 s3, s3, 6
	s_add_i32 s3, s3, s22
	v_add_u32_e32 v196, s3, v153
	v_readlane_b32 s22, v249, 12
	v_ashrrev_i32_e32 v197, 31, v196
	v_readlane_b32 s23, v249, 13
	v_lshlrev_b32_e32 v200, 2, v157
	v_add_u32_e32 v192, 16, v196
	v_lshl_add_u64 v[128:129], v[196:197], 2, s[22:23]
	global_load_dword v130, v[128:129], off
	global_load_dword v131, v[128:129], off offset:64
	global_load_dword v132, v[128:129], off offset:128
	global_load_dword v133, v[128:129], off offset:192
	global_load_dword v134, v[128:129], off offset:512
	global_load_dword v135, v[128:129], off offset:576
	global_load_dword v136, v[128:129], off offset:640
	s_nop 0
	global_load_dword v128, v[128:129], off offset:704
	v_add_u32_e32 v174, 32, v196
	v_add_u32_e32 v170, 48, v196
	v_add_u32_e32 v166, 0x80, v196
	v_add_u32_e32 v162, 0x90, v196
	v_add_u32_e32 v158, 0xa0, v196
	v_add_u32_e32 v154, 0xb0, v196
	v_ashrrev_i32_e32 v193, 31, v192
	v_ashrrev_i32_e32 v175, 31, v174
	v_ashrrev_i32_e32 v171, 31, v170
	v_ashrrev_i32_e32 v167, 31, v166
	v_ashrrev_i32_e32 v163, 31, v162
	v_ashrrev_i32_e32 v159, 31, v158
	v_ashrrev_i32_e32 v155, 31, v154
	v_lshl_add_u32 v198, s31, 5, v200
	s_cmp_gt_i32 s74, 1
	s_mov_b64 s[22:23], -1
	s_waitcnt vmcnt(0)
	v_fmamk_f32 v129, v130, 0x3a800000, v228
	v_fmamk_f32 v130, v131, 0x3a800000, v228
	v_fmamk_f32 v131, v132, 0x3a800000, v228
	v_fmamk_f32 v132, v133, 0x3a800000, v228
	v_fmamk_f32 v133, v134, 0x3a800000, v228
	v_fmamk_f32 v134, v135, 0x3a800000, v228
	v_fmamk_f32 v135, v136, 0x3a800000, v228
	v_fmamk_f32 v128, v128, 0x3a800000, v228
	v_rsq_f32_e32 v194, v129
	v_rsq_f32_e32 v190, v130
	v_rsq_f32_e32 v172, v131
	v_rsq_f32_e32 v168, v132
	v_rsq_f32_e32 v164, v133
	v_rsq_f32_e32 v160, v134
	v_rsq_f32_e32 v156, v135
	v_rsq_f32_e32 v152, v128
	s_cbranch_scc0 .LBB0_587
	s_cmpk_gt_i32 s2, 0x7f
	s_cselect_b64 s[42:43], -1, 0
	s_cmpk_lt_i32 s2, 0x80
	s_cselect_b64 s[22:23], -1, 0
	s_cmp_lt_u32 s74, 4
	s_cselect_b64 s[38:39], -1, 0
	s_mov_b64 s[2:3], -1
	s_and_b64 vcc, exec, s[38:39]
	s_cbranch_vccnz .LBB0_386
	s_and_b32 s35, s74, 0x7ffffffe
	s_cmp_lt_i32 s35, 16
	s_cbranch_scc1 .LBB0_301
	s_cmp_lg_u32 s35, 16
	s_cselect_b64 s[44:45], -1, 0
	s_cbranch_execz .LBB0_302
	s_branch .LBB0_303
